# code placement: attention ping-pong stream shifted by one 4-byte s_nop (loop head 0xFE0C, 4 mod 8) to bench the other fetch phase
# baseline (speedup 1.0000x reference)
; #define WAITBAR(N) asm volatile("s_waitcnt vmcnt(" #N ") lgkmcnt(0)\n\ts_barrier" ::: "memory")
; __device__ __forceinline__ void attn_unit(int b, int h, int qb, const bf16_t* __restrict__ proj, const float* __restrict__ btab, float lam, float outscale,
;                                           const float* __restrict__ gain, float* o1scr, bf16_t* merged, LAS char* lds) {
;     ...
;         const bf16_t* Qw = proj + (rowbase + qw + r32) * LD + OQ + hq * 64 + hi * 8;
;         float m_reg = -1e30f, l_reg = 0; f32x16 o[4]; bf16x8 qr[4];
; #pragma unroll
;         for (int d0 = 0; d0 < 4; ++d0) { o[d0] = f32x16{}; qr[d0] = *(const bf16x8*)(Qw + d0 * 16); }
;     ...
;         f32x16 pA0, pA1, pB0, pB1; float mnA, mnB, alA, alB, bo; bf16x8 pa0, pa1, pa2, pa3; constexpr int NT = T / 64;
;         asm volatile("s_waitcnt vmcnt(0) lgkmcnt(0)" ::: "memory"); __syncthreads();
;         DMA_TILE(0, 0); DMA_TILE(1, 1);
;         WAITBAR(3);
.LBB0_187:
	s_or_b32 s24, s6, s48
	s_lshl_b64 s[2:3], s[24:25], 1
	v_lshl_add_u64 v[2:3], v[190:191], 0, s[2:3]
	s_add_u32 s2, s36, s2
	s_addc_u32 s3, s37, s3
	global_load_dwordx4 v[142:145], v[2:3], off
	global_load_dwordx4 v[138:141], v[2:3], off offset:32
	global_load_dwordx4 v[134:137], v[2:3], off offset:64
	global_load_dwordx4 v[130:133], v[2:3], off offset:96
	s_nop 0
	v_lshl_add_u64 v[184:185], s[2:3], 0, v[186:187]
	s_xor_b64 s[2:3], s[0:1], -1
	s_mov_b64 s[6:7], 0x800
	v_lshl_add_u64 v[184:185], v[184:185], 0, s[6:7]
	v_mov_b64_e32 v[250:251], v[192:193]
	v_mov_b64_e32 v[246:247], v[194:195]
	s_mov_b32 s6, 0xc8000
	s_mov_b32 s7, 0
	v_readfirstlane_b32 s67, v222
	v_add_u32_e32 v239, v226, v227
	v_add_u32_e32 v240, v226, v228
	v_add_u32_e32 v241, v226, v229
	v_add_u32_e32 v242, v226, v230
	s_lshr_b32 s67, s67, 8
	v_add_u32_e32 v239, 0x14000, v239
	v_add_u32_e32 v240, 0x14000, v240
	v_add_u32_e32 v241, 0x14000, v241
	v_add_u32_e32 v242, 0x14000, v242
	v_mov_b32_e32 v243, v215
	v_bfe_u32 v244, v222, 4, 1
	v_bfe_u32 v249, v222, 6, 1
	v_sub_u32_e32 v244, v249, v244
	v_mul_i32_i24_e32 v244, 0xc800, v244
	v_ashrrev_i32_e32 v245, 31, v244
	v_lshl_add_u64 v[250:251], v[250:251], 0, v[244:245]
	v_lshl_add_u64 v[246:247], v[246:247], 0, v[244:245]
	v_mov_b32_e32 v2, 0
	v_mov_b32_e32 v3, 0
	v_mov_b32_e32 v4, 0
	v_mov_b32_e32 v5, 0
	v_mov_b32_e32 v6, 0
	v_mov_b32_e32 v7, 0
	v_mov_b32_e32 v8, 0
	v_mov_b32_e32 v9, 0
	v_mov_b32_e32 v10, 0
	v_mov_b32_e32 v11, 0
	v_mov_b32_e32 v12, 0
	v_mov_b32_e32 v13, 0
	v_mov_b32_e32 v14, 0
	v_mov_b32_e32 v15, 0
	v_mov_b32_e32 v16, 0
	v_mov_b32_e32 v17, 0
	v_mov_b32_e32 v18, 0
	v_mov_b32_e32 v19, 0
	v_mov_b32_e32 v20, 0
	v_mov_b32_e32 v21, 0
	v_mov_b32_e32 v22, 0
	v_mov_b32_e32 v23, 0
	v_mov_b32_e32 v24, 0
	v_mov_b32_e32 v25, 0
	v_mov_b32_e32 v26, 0
	v_mov_b32_e32 v27, 0
	v_mov_b32_e32 v28, 0
	v_mov_b32_e32 v29, 0
	v_mov_b32_e32 v30, 0
	v_mov_b32_e32 v31, 0
	v_mov_b32_e32 v32, 0
	v_mov_b32_e32 v33, 0
	v_mov_b32_e32 v34, 0
	v_mov_b32_e32 v35, 0
	v_mov_b32_e32 v36, 0
	v_mov_b32_e32 v37, 0
	v_mov_b32_e32 v38, 0
	v_mov_b32_e32 v39, 0
	v_mov_b32_e32 v40, 0
	v_mov_b32_e32 v41, 0
	v_mov_b32_e32 v42, 0
	v_mov_b32_e32 v43, 0
	v_mov_b32_e32 v44, 0
	v_mov_b32_e32 v45, 0
	v_mov_b32_e32 v46, 0
	v_mov_b32_e32 v47, 0
	v_mov_b32_e32 v48, 0
	v_mov_b32_e32 v49, 0
	v_mov_b32_e32 v50, 0
	v_mov_b32_e32 v51, 0
	v_mov_b32_e32 v52, 0
	v_mov_b32_e32 v53, 0
	v_mov_b32_e32 v54, 0
	v_mov_b32_e32 v55, 0
	v_mov_b32_e32 v56, 0
	v_mov_b32_e32 v57, 0
	v_mov_b32_e32 v58, 0
	v_mov_b32_e32 v59, 0
	v_mov_b32_e32 v60, 0
	v_mov_b32_e32 v61, 0
	v_mov_b32_e32 v62, 0
	v_mov_b32_e32 v63, 0
	v_mov_b32_e32 v64, 0
	v_mov_b32_e32 v65, 0
	v_mov_b32_e32 v238, 0
	v_add_u32_e32 v245, 0xffffff00, v235
	s_sub_i32 s65, s78, 0x80
	s_mov_b32 s40, 0
	s_waitcnt lgkmcnt(0)
	s_barrier
	s_mov_b32 s24, 0
	s_lshl_b32 s12, s24, 13
	s_add_i32 s12, s12, s66
	s_lshl_b32 s13, s24, 14
	s_add_i32 s13, s13, s74
	s_add_i32 m0, s12, 0x14000
	s_nop 0
	global_load_lds_dwordx4 v[184:185], off
	s_mov_b32 m0, s13
	v_lshl_add_u64 v[184:185], v[184:185], 0, s[6:7]
	global_load_lds_dwordx4 v[250:251], off
	s_add_i32 m0, s13, 0x400
	v_lshl_add_u64 v[250:251], v[250:251], 0, s[6:7]
	global_load_lds_dwordx4 v[246:247], off
	v_lshl_add_u64 v[246:247], v[246:247], 0, s[6:7]
	s_mov_b32 s24, 1
	s_lshl_b32 s12, s24, 13
	s_add_i32 s12, s12, s66
	s_lshl_b32 s13, s24, 14
	s_add_i32 s13, s13, s74
	s_add_i32 m0, s12, 0x14000
	s_nop 0
	global_load_lds_dwordx4 v[184:185], off
	s_mov_b32 m0, s13
	v_lshl_add_u64 v[184:185], v[184:185], 0, s[6:7]
	global_load_lds_dwordx4 v[250:251], off
	s_add_i32 m0, s13, 0x400
	v_lshl_add_u64 v[250:251], v[250:251], 0, s[6:7]
	global_load_lds_dwordx4 v[246:247], off
	v_lshl_add_u64 v[246:247], v[246:247], 0, s[6:7]
	s_waitcnt vmcnt(3)
	s_barrier
	s_cmp_eq_u32 s67, 0
	s_cbranch_scc1 .Lat_enter
	s_barrier
	s_setprio 1
